# grid barrier: XCD leader skips the L2 write-back after out-proj/up/down GEMM phases (same-XCD producer/consumer tiles, write-through sample-row stores, runtime XCC-mapping check); init_rows param load
# speedup vs baseline: 1.0377x; 1.0072x over previous
.LBB0_976:
	s_mov_b64 s[40:41], -1
	s_mov_b64 s[42:43], 0
	s_cmp_lt_i32 s30, 3
	s_mov_b64 s[64:65], 0
	s_cbranch_scc1 .LBB0_984
	s_cmp_gt_i32 s30, 3
	s_cbranch_scc0 .LBB0_981
	s_cmp_eq_u32 s30, 4
	s_mov_b64 s[64:65], -1
	s_cbranch_scc0 .LBB0_980
	v_readlane_b32 s36, v254, 36
	v_lshlrev_b64 v[6:7], 11, v[8:9]
	v_readlane_b32 s37, v254, 37
	v_ashrrev_i32_e32 v11, 31, v10
	v_cvt_pk_bf16_f32 v4, v0, v1
	v_lshl_add_u64 v[6:7], s[36:37], 0, v[6:7]
	v_cvt_pk_bf16_f32 v5, v2, v3
	v_lshl_add_u64 v[6:7], v[10:11], 1, v[6:7]
	global_store_dwordx2 v[6:7], v[4:5], off sc1
	s_mov_b64 s[64:65], 0

.LBB0_981:
	s_and_b64 vcc, exec, s[40:41]
	s_cbranch_vccz .LBB0_983
	v_max_f32_e32 v4, v0, v0
	v_max_f32_e32 v5, v1, v1
	v_max_f32_e32 v6, v2, v2
	v_max_f32_e32 v7, v3, v3
	v_max_f32_e32 v4, 0, v4
	v_max_f32_e32 v5, 0, v5
	v_max_f32_e32 v6, 0, v6
	v_max_f32_e32 v7, 0, v7
	v_pk_mul_f32 v[4:5], v[4:5], v[4:5]
	v_pk_mul_f32 v[6:7], v[6:7], v[6:7]
	v_cvt_pk_bf16_f32 v4, v4, v5
	v_cvt_pk_bf16_f32 v5, v6, v7
	v_lshlrev_b64 v[6:7], 13, v[8:9]
	v_lshl_add_u64 v[6:7], s[22:23], 0, v[6:7]
	v_ashrrev_i32_e32 v11, 31, v10
	v_lshl_add_u64 v[6:7], v[10:11], 1, v[6:7]
	global_store_dwordx2 v[6:7], v[4:5], off sc1

.Lsr_nopre:
	s_waitcnt vmcnt(0)
	v_pk_fma_f32 v[4:5], v[0:1], v[18:19], v[4:5]
	v_lshlrev_b64 v[18:19], 12, v[12:13]
	v_lshl_add_u64 v[18:19], s[18:19], 0, v[18:19]
	v_pk_fma_f32 v[6:7], v[2:3], v[20:21], v[6:7]
	v_lshl_add_u64 v[18:19], v[18:19], 0, v[16:17]
	global_store_dwordx4 v[18:19], v[4:7], off sc1
	s_cbranch_vccnz .LBB0_1000
	v_readlane_b32 s36, v255, 3
	v_readlane_b32 s37, v255, 4
	v_lshlrev_b64 v[18:19], 10, v[12:13]
	s_andn2_b64 vcc, exec, s[8:9]
	v_readlane_b32 s36, v255, 1
	v_readlane_b32 s37, v255, 2
	v_pk_mul_f32 v[22:23], v[6:7], v[52:53]
	v_pk_mul_f32 v[20:21], v[4:5], v[50:51]
	v_pk_add_f32 v[26:27], v[56:57], 1.0 op_sel_hi:[1,0]
	v_pk_add_f32 v[24:25], v[54:55], 1.0 op_sel_hi:[1,0]
	v_pk_mul_f32 v[22:23], v[22:23], v[26:27]
	v_pk_mul_f32 v[20:21], v[20:21], v[24:25]
	s_nop 0
	v_cvt_pk_bf16_f32 v20, v20, v21
	v_cvt_pk_bf16_f32 v21, v22, v23
	v_lshl_add_u64 v[22:23], v[18:19], 1, s[46:47]
	v_lshl_add_u64 v[22:23], v[10:11], 1, v[22:23]
	global_store_dwordx2 v[22:23], v[20:21], off sc1
	s_cbranch_vccnz .LBB0_997
	v_readlane_b32 s36, v254, 59
	v_readlane_b32 s37, v254, 60
	s_nop 1
	v_readlane_b32 s36, v254, 61
	v_readlane_b32 s37, v254, 62
	v_pk_mul_f32 v[22:23], v[6:7], v[60:61]
	v_readlane_b32 s36, v254, 63
	v_readlane_b32 s37, v255, 0
	v_pk_mul_f32 v[20:21], v[4:5], v[58:59]
	v_pk_add_f32 v[16:17], v[64:65], 1.0 op_sel_hi:[1,0]
	v_pk_add_f32 v[14:15], v[62:63], 1.0 op_sel_hi:[1,0]
	v_lshl_add_u64 v[18:19], v[18:19], 1, s[36:37]
	v_pk_mul_f32 v[16:17], v[22:23], v[16:17]
	v_pk_mul_f32 v[14:15], v[20:21], v[14:15]
	s_nop 0
	v_cvt_pk_bf16_f32 v14, v14, v15
	v_cvt_pk_bf16_f32 v15, v16, v17
	v_lshl_add_u64 v[16:17], v[10:11], 1, v[18:19]
	global_store_dwordx2 v[16:17], v[14:15], off sc1

.LBB0_1003:
	s_and_b64 vcc, exec, s[64:65]
	s_mov_b32 s64, 0xf000
	s_cbranch_vccz .LBB0_1007
	s_andn2_b64 vcc, exec, s[10:11]
	s_cbranch_vccnz .LBB0_1006
	v_readlane_b32 s36, v254, 47
	s_waitcnt lgkmcnt(0)
	v_lshlrev_b64 v[4:5], 11, v[8:9]
	v_readlane_b32 s37, v254, 48
	v_ashrrev_i32_e32 v11, 31, v10
	s_nop 0
	v_lshl_add_u64 v[4:5], s[36:37], 0, v[4:5]
	v_lshl_add_u64 v[4:5], v[10:11], 2, v[4:5]
	global_store_dwordx4 v[4:5], v[0:3], off sc1

.LBB0_1007:
	s_andn2_b64 vcc, exec, s[42:43]
	s_cbranch_vccnz .LBB0_1020
	s_ashr_i32 s35, s29, 6
	v_and_b32_e32 v10, 0x3fc, v10
	s_waitcnt lgkmcnt(0)
	v_lshlrev_b64 v[4:5], 10, v[8:9]
	v_or_b32_e32 v4, v4, v10
	s_mov_b64 s[64:65], -1
	s_mov_b64 s[40:41], 0
	s_cmp_lt_i32 s35, 2
	s_mov_b64 s[42:43], 0
	s_cbranch_scc1 .LBB0_1012
	s_cmp_eq_u32 s35, 2
	s_mov_b64 s[42:43], -1
	s_cbranch_scc0 .LBB0_1011
	v_readlane_b32 s36, v255, 13
	v_readlane_b32 s37, v255, 14
	v_cvt_pk_bf16_f32 v6, v0, v1
	v_cvt_pk_bf16_f32 v7, v2, v3
	v_lshl_add_u64 v[8:9], v[4:5], 1, s[36:37]
	global_store_dwordx2 v[8:9], v[6:7], off sc1
	s_mov_b64 s[42:43], 0

.LBB0_1014:
	s_andn2_b64 vcc, exec, s[42:43]
	v_mul_f32_e32 v9, 0xbfb8aa3b, v0
	v_mul_f32_e32 v8, 0xbfb8aa3b, v1
	v_mul_f32_e32 v7, 0xbfb8aa3b, v2
	v_mul_f32_e32 v6, 0xbfb8aa3b, v3
	s_mov_b32 s64, 0xf000
	s_cbranch_vccnz .LBB0_1016
	v_exp_f32_e32 v11, v9
	s_cmpk_lt_u32 s28, 0x400
	s_cselect_b32 s35, s23, s55
	s_cselect_b32 s36, s22, s54
	v_add_f32_e32 v11, 1.0, v11
	v_rcp_f32_e32 v14, v11
	v_exp_f32_e32 v11, v8
	v_mov_b32_e32 v12, s36
	v_mov_b32_e32 v13, s35
	s_mov_b64 s[40:41], 0
	v_add_f32_e32 v11, 1.0, v11
	v_rcp_f32_e32 v15, v11
	s_nop 0
	v_pk_mul_f32 v[0:1], v[0:1], v[14:15]
	s_nop 0
	v_cvt_pk_bf16_f32 v0, v0, v1
	v_exp_f32_e32 v1, v7
	s_nop 0
	v_add_f32_e32 v1, 1.0, v1
	v_rcp_f32_e32 v14, v1
	v_exp_f32_e32 v1, v6
	s_nop 0
	v_add_f32_e32 v1, 1.0, v1
	v_rcp_f32_e32 v15, v1
	s_nop 0
	v_pk_mul_f32 v[2:3], v[2:3], v[14:15]
	s_nop 0
	v_cvt_pk_bf16_f32 v1, v2, v3
	v_lshl_add_u64 v[2:3], v[4:5], 1, v[12:13]
	global_store_dwordx2 v[2:3], v[0:1], off sc1

.LBB0_1019:
	v_exp_f32_e32 v9, v9
	v_sub_f32_e32 v10, 1.0, v1
	v_add_f32_e32 v9, 1.0, v9
	v_rcp_f32_e32 v9, v9
	s_nop 0
	v_fmac_f32_e32 v1, v9, v10
	v_log_f32_e32 v10, v1
	v_exp_f32_e32 v1, v8
	v_sub_f32_e32 v8, 1.0, v3
	v_add_f32_e32 v1, 1.0, v1
	v_rcp_f32_e32 v1, v1
	s_nop 0
	v_fmac_f32_e32 v3, v1, v8
	v_exp_f32_e32 v1, v7
	v_log_f32_e32 v11, v3
	v_sub_f32_e32 v3, 1.0, v0
	v_add_f32_e32 v1, 1.0, v1
	v_rcp_f32_e32 v1, v1
	s_nop 0
	v_fmac_f32_e32 v0, v1, v3
	v_log_f32_e32 v12, v0
	v_exp_f32_e32 v0, v6
	v_sub_f32_e32 v1, 1.0, v2
	v_add_f32_e32 v0, 1.0, v0
	v_rcp_f32_e32 v0, v0
	s_nop 0
	v_fmac_f32_e32 v2, v0, v1
	v_log_f32_e32 v13, v2
	v_lshl_add_u64 v[0:1], v[4:5], 2, s[18:19]
	global_store_dwordx4 v[0:1], v[10:13], off sc1

.LBB0_1032:
	s_mov_b64 s[40:41], -1
	s_mov_b64 s[42:43], 0
	s_cmp_lt_i32 s30, 3
	s_mov_b64 s[62:63], 0
	s_cbranch_scc1 .LBB0_1040
	s_cmp_gt_i32 s30, 3
	s_cbranch_scc0 .LBB0_1037
	s_cmp_eq_u32 s30, 4
	s_mov_b64 s[62:63], -1
	s_cbranch_scc0 .LBB0_1036
	v_readlane_b32 s36, v254, 36
	v_lshlrev_b64 v[6:7], 11, v[8:9]
	v_readlane_b32 s37, v254, 37
	v_ashrrev_i32_e32 v11, 31, v10
	v_cvt_pk_bf16_f32 v4, v0, v1
	v_lshl_add_u64 v[6:7], s[36:37], 0, v[6:7]
	v_cvt_pk_bf16_f32 v5, v2, v3
	v_lshl_add_u64 v[6:7], v[10:11], 1, v[6:7]
	global_store_dwordx2 v[6:7], v[4:5], off sc1
	s_mov_b64 s[62:63], 0

.LBB0_1050:
	v_cmp_gt_i32_e32 vcc, 0, v192
	v_ashrrev_i32_e32 v6, 12, v8
	v_add_u32_e32 v7, 4, v192
	v_cndmask_b32_e32 v6, v7, v6, vcc
	s_movk_i32 s35, 0x6800
	v_mad_i64_i32 v[14:15], s[36:37], v6, s35, 0
	v_readlane_b32 s36, v255, 15
	v_ashrrev_i32_e32 v11, 31, v10
	v_readlane_b32 s37, v255, 16
	v_lshlrev_b64 v[16:17], 2, v[10:11]
	v_lshl_add_u64 v[4:5], v[4:5], 0, v[16:17]
	v_lshl_add_u64 v[18:19], v[14:15], 2, s[36:37]
	v_lshl_add_u64 v[18:19], v[18:19], 0, v[16:17]
	global_load_dwordx4 v[4:7], v[4:5], off
	s_andn2_b64 vcc, exec, s[6:7]
	global_load_dwordx4 v[18:21], v[18:19], off
	s_waitcnt vmcnt(0)
	v_pk_fma_f32 v[4:5], v[0:1], v[18:19], v[4:5]
	v_lshlrev_b64 v[18:19], 12, v[12:13]
	v_lshl_add_u64 v[18:19], s[18:19], 0, v[18:19]
	v_pk_fma_f32 v[6:7], v[2:3], v[20:21], v[6:7]
	v_lshl_add_u64 v[18:19], v[18:19], 0, v[16:17]
	global_store_dwordx4 v[18:19], v[4:7], off sc1
	s_cbranch_vccnz .LBB0_1056
	v_readlane_b32 s36, v255, 3
	v_readlane_b32 s37, v255, 4
	v_lshlrev_b64 v[18:19], 10, v[12:13]
	s_andn2_b64 vcc, exec, s[8:9]
	v_lshl_add_u64 v[20:21], s[36:37], 0, v[16:17]
	v_readlane_b32 s36, v255, 1
	v_readlane_b32 s37, v255, 2
	global_load_dwordx4 v[20:23], v[20:21], off
	s_waitcnt vmcnt(0)
	v_pk_mul_f32 v[22:23], v[6:7], v[22:23]
	v_lshl_add_u64 v[24:25], v[14:15], 2, s[36:37]
	v_lshl_add_u64 v[24:25], v[24:25], 0, v[16:17]
	global_load_dwordx4 v[24:27], v[24:25], off
	v_pk_mul_f32 v[20:21], v[4:5], v[20:21]
	s_waitcnt vmcnt(0)
	v_pk_add_f32 v[26:27], v[26:27], 1.0 op_sel_hi:[1,0]
	v_pk_add_f32 v[24:25], v[24:25], 1.0 op_sel_hi:[1,0]
	v_pk_mul_f32 v[22:23], v[22:23], v[26:27]
	v_pk_mul_f32 v[20:21], v[20:21], v[24:25]
	s_nop 0
	v_cvt_pk_bf16_f32 v20, v20, v21
	v_cvt_pk_bf16_f32 v21, v22, v23
	v_lshl_add_u64 v[22:23], v[18:19], 1, s[46:47]
	v_lshl_add_u64 v[22:23], v[10:11], 1, v[22:23]
	global_store_dwordx2 v[22:23], v[20:21], off sc1
	s_cbranch_vccnz .LBB0_1053
	v_readlane_b32 s36, v254, 59
	v_readlane_b32 s37, v254, 60
	s_nop 1
	v_lshl_add_u64 v[20:21], s[36:37], 0, v[16:17]
	v_readlane_b32 s36, v254, 61
	v_readlane_b32 s37, v254, 62
	global_load_dwordx4 v[20:23], v[20:21], off
	s_waitcnt vmcnt(0)
	v_pk_mul_f32 v[22:23], v[6:7], v[22:23]
	v_lshl_add_u64 v[14:15], v[14:15], 2, s[36:37]
	v_lshl_add_u64 v[14:15], v[14:15], 0, v[16:17]
	global_load_dwordx4 v[14:17], v[14:15], off
	v_readlane_b32 s36, v254, 63
	v_readlane_b32 s37, v255, 0
	v_pk_mul_f32 v[20:21], v[4:5], v[20:21]
	s_waitcnt vmcnt(0)
	v_pk_add_f32 v[16:17], v[16:17], 1.0 op_sel_hi:[1,0]
	v_pk_add_f32 v[14:15], v[14:15], 1.0 op_sel_hi:[1,0]
	v_lshl_add_u64 v[18:19], v[18:19], 1, s[36:37]
	v_pk_mul_f32 v[16:17], v[22:23], v[16:17]
	v_pk_mul_f32 v[14:15], v[20:21], v[14:15]
	s_nop 0
	v_cvt_pk_bf16_f32 v14, v14, v15
	v_cvt_pk_bf16_f32 v15, v16, v17
	v_lshl_add_u64 v[16:17], v[10:11], 1, v[18:19]
	global_store_dwordx2 v[16:17], v[14:15], off sc1

.LBB0_1059:
	s_and_b64 vcc, exec, s[62:63]
	s_cbranch_vccz .LBB0_1063
	s_andn2_b64 vcc, exec, s[10:11]
	s_cbranch_vccnz .LBB0_1062
	v_readlane_b32 s36, v254, 47
	s_waitcnt lgkmcnt(0)
	v_lshlrev_b64 v[4:5], 11, v[8:9]
	v_readlane_b32 s37, v254, 48
	v_ashrrev_i32_e32 v11, 31, v10
	s_nop 0
	v_lshl_add_u64 v[4:5], s[36:37], 0, v[4:5]
	v_lshl_add_u64 v[4:5], v[10:11], 2, v[4:5]
	global_store_dwordx4 v[4:5], v[0:3], off sc1

.LBB0_1063:
	s_andn2_b64 vcc, exec, s[42:43]
	s_cbranch_vccnz .LBB0_1076
	s_ashr_i32 s35, s29, 6
	v_and_b32_e32 v10, 0x3fc, v10
	s_waitcnt lgkmcnt(0)
	v_lshlrev_b64 v[4:5], 10, v[8:9]
	v_or_b32_e32 v4, v4, v10
	s_mov_b64 s[62:63], -1
	s_mov_b64 s[40:41], 0
	s_cmp_lt_i32 s35, 2
	s_mov_b64 s[42:43], 0
	s_cbranch_scc1 .LBB0_1068
	s_cmp_eq_u32 s35, 2
	s_mov_b64 s[42:43], -1
	s_cbranch_scc0 .LBB0_1067
	v_readlane_b32 s36, v255, 13
	v_readlane_b32 s37, v255, 14
	v_cvt_pk_bf16_f32 v6, v0, v1
	v_cvt_pk_bf16_f32 v7, v2, v3
	v_lshl_add_u64 v[8:9], v[4:5], 1, s[36:37]
	global_store_dwordx2 v[8:9], v[6:7], off sc1
	s_mov_b64 s[42:43], 0

.LBB0_1070:
	s_andn2_b64 vcc, exec, s[42:43]
	v_mul_f32_e32 v9, 0xbfb8aa3b, v0
	v_mul_f32_e32 v8, 0xbfb8aa3b, v1
	v_mul_f32_e32 v7, 0xbfb8aa3b, v2
	v_mul_f32_e32 v6, 0xbfb8aa3b, v3
	s_cbranch_vccnz .LBB0_1072
	v_exp_f32_e32 v11, v9
	s_cmpk_lt_u32 s28, 0x400
	s_cselect_b32 s35, s23, s55
	s_cselect_b32 s36, s22, s54
	v_add_f32_e32 v11, 1.0, v11
	v_rcp_f32_e32 v14, v11
	v_exp_f32_e32 v11, v8
	v_mov_b32_e32 v12, s36
	v_mov_b32_e32 v13, s35
	s_mov_b64 s[40:41], 0
	v_add_f32_e32 v11, 1.0, v11
	v_rcp_f32_e32 v15, v11
	s_nop 0
	v_pk_mul_f32 v[0:1], v[0:1], v[14:15]
	s_nop 0
	v_cvt_pk_bf16_f32 v0, v0, v1
	v_exp_f32_e32 v1, v7
	s_nop 0
	v_add_f32_e32 v1, 1.0, v1
	v_rcp_f32_e32 v14, v1
	v_exp_f32_e32 v1, v6
	s_nop 0
	v_add_f32_e32 v1, 1.0, v1
	v_rcp_f32_e32 v15, v1
	s_nop 0
	v_pk_mul_f32 v[2:3], v[2:3], v[14:15]
	s_nop 0
	v_cvt_pk_bf16_f32 v1, v2, v3
	v_lshl_add_u64 v[2:3], v[4:5], 1, v[12:13]
	global_store_dwordx2 v[2:3], v[0:1], off sc1

.LBB0_1086:
	s_mov_b64 s[40:41], -1
	s_mov_b64 s[42:43], 0
	s_cmp_lt_i32 s30, 3
	s_mov_b64 s[12:13], 0
	s_cbranch_scc1 .LBB0_1094
	s_cmp_gt_i32 s30, 3
	s_cbranch_scc0 .LBB0_1091
	s_cmp_eq_u32 s30, 4
	s_mov_b64 s[12:13], -1
	s_cbranch_scc0 .LBB0_1090
	v_readlane_b32 s12, v254, 36
	v_lshlrev_b64 v[6:7], 11, v[8:9]
	v_readlane_b32 s13, v254, 37
	v_ashrrev_i32_e32 v11, 31, v10
	v_cvt_pk_bf16_f32 v4, v0, v1
	v_lshl_add_u64 v[6:7], s[12:13], 0, v[6:7]
	v_cvt_pk_bf16_f32 v5, v2, v3
	v_lshl_add_u64 v[6:7], v[10:11], 1, v[6:7]
	global_store_dwordx2 v[6:7], v[4:5], off sc1
	s_mov_b64 s[12:13], 0

.LBB0_1104:
	v_cmp_gt_i32_e32 vcc, s5, v8
	v_ashrrev_i32_e32 v6, 12, v8
	v_add_u32_e32 v7, 0xffffc004, v8
	v_cndmask_b32_e32 v6, v7, v6, vcc
	s_movk_i32 s31, 0x6800
	v_mad_i64_i32 v[14:15], s[34:35], v6, s31, 0
	v_readlane_b32 s34, v255, 15
	v_ashrrev_i32_e32 v11, 31, v10
	v_readlane_b32 s35, v255, 16
	v_lshlrev_b64 v[16:17], 2, v[10:11]
	v_lshl_add_u64 v[4:5], v[4:5], 0, v[16:17]
	v_lshl_add_u64 v[18:19], v[14:15], 2, s[34:35]
	v_lshl_add_u64 v[18:19], v[18:19], 0, v[16:17]
	global_load_dwordx4 v[4:7], v[4:5], off
	s_andn2_b64 vcc, exec, s[6:7]
	global_load_dwordx4 v[18:21], v[18:19], off
	s_waitcnt vmcnt(0)
	v_pk_fma_f32 v[4:5], v[0:1], v[18:19], v[4:5]
	v_lshlrev_b64 v[18:19], 12, v[12:13]
	v_lshl_add_u64 v[18:19], s[18:19], 0, v[18:19]
	v_pk_fma_f32 v[6:7], v[2:3], v[20:21], v[6:7]
	v_lshl_add_u64 v[18:19], v[18:19], 0, v[16:17]
	global_store_dwordx4 v[18:19], v[4:7], off sc1
	s_cbranch_vccnz .LBB0_1110
	v_readlane_b32 s34, v255, 3
	v_readlane_b32 s35, v255, 4
	v_lshlrev_b64 v[18:19], 10, v[12:13]
	s_andn2_b64 vcc, exec, s[8:9]
	v_lshl_add_u64 v[20:21], s[34:35], 0, v[16:17]
	v_readlane_b32 s34, v255, 1
	v_readlane_b32 s35, v255, 2
	global_load_dwordx4 v[20:23], v[20:21], off
	s_waitcnt vmcnt(0)
	v_pk_mul_f32 v[22:23], v[6:7], v[22:23]
	v_lshl_add_u64 v[24:25], v[14:15], 2, s[34:35]
	v_lshl_add_u64 v[24:25], v[24:25], 0, v[16:17]
	global_load_dwordx4 v[24:27], v[24:25], off
	v_pk_mul_f32 v[20:21], v[4:5], v[20:21]
	s_waitcnt vmcnt(0)
	v_pk_add_f32 v[26:27], v[26:27], 1.0 op_sel_hi:[1,0]
	v_pk_add_f32 v[24:25], v[24:25], 1.0 op_sel_hi:[1,0]
	v_pk_mul_f32 v[22:23], v[22:23], v[26:27]
	v_pk_mul_f32 v[20:21], v[20:21], v[24:25]
	s_nop 0
	v_cvt_pk_bf16_f32 v20, v20, v21
	v_cvt_pk_bf16_f32 v21, v22, v23
	v_lshl_add_u64 v[22:23], v[18:19], 1, s[46:47]
	v_lshl_add_u64 v[22:23], v[10:11], 1, v[22:23]
	global_store_dwordx2 v[22:23], v[20:21], off sc1
	s_cbranch_vccnz .LBB0_1107
	v_readlane_b32 s34, v254, 59
	v_readlane_b32 s35, v254, 60
	s_nop 1
	v_lshl_add_u64 v[20:21], s[34:35], 0, v[16:17]
	v_readlane_b32 s34, v254, 61
	v_readlane_b32 s35, v254, 62
	global_load_dwordx4 v[20:23], v[20:21], off
	s_waitcnt vmcnt(0)
	v_pk_mul_f32 v[22:23], v[6:7], v[22:23]
	v_lshl_add_u64 v[14:15], v[14:15], 2, s[34:35]
	v_lshl_add_u64 v[14:15], v[14:15], 0, v[16:17]
	global_load_dwordx4 v[14:17], v[14:15], off
	v_readlane_b32 s34, v254, 63
	v_readlane_b32 s35, v255, 0
	v_pk_mul_f32 v[20:21], v[4:5], v[20:21]
	s_waitcnt vmcnt(0)
	v_pk_add_f32 v[16:17], v[16:17], 1.0 op_sel_hi:[1,0]
	v_pk_add_f32 v[14:15], v[14:15], 1.0 op_sel_hi:[1,0]
	v_lshl_add_u64 v[18:19], v[18:19], 1, s[34:35]
	v_pk_mul_f32 v[16:17], v[22:23], v[16:17]
	v_pk_mul_f32 v[14:15], v[20:21], v[14:15]
	s_nop 0
	v_cvt_pk_bf16_f32 v14, v14, v15
	v_cvt_pk_bf16_f32 v15, v16, v17
	v_lshl_add_u64 v[16:17], v[10:11], 1, v[18:19]
	global_store_dwordx2 v[16:17], v[14:15], off sc1

.LBB0_1113:
	s_and_b64 vcc, exec, s[12:13]
	s_cbranch_vccz .LBB0_1117
	s_andn2_b64 vcc, exec, s[10:11]
	s_cbranch_vccnz .LBB0_1116
	v_readlane_b32 s10, v254, 47
	s_waitcnt lgkmcnt(0)
	v_lshlrev_b64 v[4:5], 11, v[8:9]
	v_readlane_b32 s11, v254, 48
	v_ashrrev_i32_e32 v11, 31, v10
	s_nop 0
	v_lshl_add_u64 v[4:5], s[10:11], 0, v[4:5]
	v_lshl_add_u64 v[4:5], v[10:11], 2, v[4:5]
	global_store_dwordx4 v[4:5], v[0:3], off sc1

.LBB0_1117:
	s_andn2_b64 vcc, exec, s[42:43]
	s_cbranch_vccnz .LBB0_960
	s_ashr_i32 s29, s29, 6
	v_and_b32_e32 v10, 0x3fc, v10
	s_waitcnt lgkmcnt(0)
	v_lshlrev_b64 v[4:5], 10, v[8:9]
	v_or_b32_e32 v4, v4, v10
	s_mov_b64 s[40:41], -1
	s_mov_b64 s[10:11], 0
	s_cmp_lt_i32 s29, 2
	s_mov_b64 s[12:13], 0
	s_cbranch_scc1 .LBB0_1122
	s_cmp_eq_u32 s29, 2
	s_mov_b64 s[12:13], -1
	s_cbranch_scc0 .LBB0_1121
	v_readlane_b32 s12, v255, 13
	v_readlane_b32 s13, v255, 14
	v_cvt_pk_bf16_f32 v6, v0, v1
	v_cvt_pk_bf16_f32 v7, v2, v3
	v_lshl_add_u64 v[8:9], v[4:5], 1, s[12:13]
	global_store_dwordx2 v[8:9], v[6:7], off sc1
	s_mov_b64 s[12:13], 0

.LBB0_1124:
	s_andn2_b64 vcc, exec, s[12:13]
	v_mul_f32_e32 v9, 0xbfb8aa3b, v0
	v_mul_f32_e32 v8, 0xbfb8aa3b, v1
	v_mul_f32_e32 v7, 0xbfb8aa3b, v2
	v_mul_f32_e32 v6, 0xbfb8aa3b, v3
	s_cbranch_vccnz .LBB0_1126
	v_exp_f32_e32 v11, v9
	s_cmpk_lt_u32 s28, 0x400
	s_cselect_b32 s10, s23, s55
	s_cselect_b32 s11, s22, s54
	v_add_f32_e32 v11, 1.0, v11
	v_rcp_f32_e32 v14, v11
	v_exp_f32_e32 v11, v8
	v_mov_b32_e32 v12, s11
	v_mov_b32_e32 v13, s10
	s_mov_b64 s[10:11], 0
	v_add_f32_e32 v11, 1.0, v11
	v_rcp_f32_e32 v15, v11
	s_nop 0
	v_pk_mul_f32 v[0:1], v[0:1], v[14:15]
	s_nop 0
	v_cvt_pk_bf16_f32 v0, v0, v1
	v_exp_f32_e32 v1, v7
	s_nop 0
	v_add_f32_e32 v1, 1.0, v1
	v_rcp_f32_e32 v14, v1
	v_exp_f32_e32 v1, v6
	s_nop 0
	v_add_f32_e32 v1, 1.0, v1
	v_rcp_f32_e32 v15, v1
	s_nop 0
	v_pk_mul_f32 v[2:3], v[2:3], v[14:15]
	s_nop 0
	v_cvt_pk_bf16_f32 v1, v2, v3
	v_lshl_add_u64 v[2:3], v[4:5], 1, v[12:13]
	global_store_dwordx2 v[2:3], v[0:1], off sc1

.LBB0_1135:
	s_andn2_b64 vcc, exec, s[2:3]
	s_mov_b32 s6, 2
	v_readlane_b32 s57, v254, 8
	v_readlane_b32 s58, v254, 9
	s_cbranch_vccnz .LBB0_1223
	s_mov_b64 s[2:3], s[52:53]
	s_getreg_b32 s6, hwreg(HW_REG_XCC_ID, 0, 4)
	s_waitcnt vmcnt(0)
	s_waitcnt vmcnt(0)
	s_barrier
	s_mov_b64 s[0:1], exec
	v_readlane_b32 s8, v253, 57
	v_readlane_b32 s9, v253, 58
	s_and_b64 s[8:9], s[0:1], s[8:9]
	s_mov_b64 exec, s[8:9]
	s_cbranch_execz .LBB0_1222
	s_add_i32 s49, 0, 0x20000
	v_mov_b32_e32 v0, s49
	s_load_dwordx2 s[2:3], s[2:3], 0xd8
	s_waitcnt vmcnt(0) expcnt(0) lgkmcnt(0)
	s_cmp_lg_u32 s54, 0
	s_cbranch_scc1 .Lxb_en_done
	v_mov_b32_e32 v20, 0x1b069000
	global_load_dword v21, v20, s[2:3] offset:1088 sc1
	global_load_dword v22, v20, s[2:3] offset:1344 sc1
	global_load_dword v23, v20, s[2:3] offset:1600 sc1
	global_load_dword v24, v20, s[2:3] offset:1856 sc1
	global_load_dword v25, v20, s[2:3] offset:2112 sc1
	global_load_dword v26, v20, s[2:3] offset:2368 sc1
	global_load_dword v27, v20, s[2:3] offset:2624 sc1
	global_load_dword v28, v20, s[2:3] offset:2880 sc1
	global_load_dword v29, v20, s[2:3] offset:1024 sc1
	global_load_dword v30, v20, s[2:3] offset:1280 sc1
	global_load_dword v31, v20, s[2:3] offset:1536 sc1
	global_load_dword v32, v20, s[2:3] offset:1792 sc1
	global_load_dword v33, v20, s[2:3] offset:2048 sc1
	global_load_dword v34, v20, s[2:3] offset:2304 sc1
	global_load_dword v35, v20, s[2:3] offset:2560 sc1
	global_load_dword v36, v20, s[2:3] offset:2816 sc1
	v_mov_b32_e32 v40, 0
	v_mov_b32_e32 v41, 0
	s_waitcnt vmcnt(0)
	v_add_u32_e32 v42, -1, v21
	v_and_b32_e32 v42, v42, v21
	v_or_b32_e32 v40, v40, v42
	v_or_b32_e32 v41, v41, v21
	v_add_u32_e32 v42, -1, v22
	v_and_b32_e32 v42, v42, v22
	v_or_b32_e32 v40, v40, v42
	v_or_b32_e32 v41, v41, v22
	v_add_u32_e32 v42, -1, v23
	v_and_b32_e32 v42, v42, v23
	v_or_b32_e32 v40, v40, v42
	v_or_b32_e32 v41, v41, v23
	v_add_u32_e32 v42, -1, v24
	v_and_b32_e32 v42, v42, v24
	v_or_b32_e32 v40, v40, v42
	v_or_b32_e32 v41, v41, v24
	v_add_u32_e32 v42, -1, v25
	v_and_b32_e32 v42, v42, v25
	v_or_b32_e32 v40, v40, v42
	v_or_b32_e32 v41, v41, v25
	v_add_u32_e32 v42, -1, v26
	v_and_b32_e32 v42, v42, v26
	v_or_b32_e32 v40, v40, v42
	v_or_b32_e32 v41, v41, v26
	v_add_u32_e32 v42, -1, v27
	v_and_b32_e32 v42, v42, v27
	v_or_b32_e32 v40, v40, v42
	v_or_b32_e32 v41, v41, v27
	v_add_u32_e32 v42, -1, v28
	v_and_b32_e32 v42, v42, v28
	v_or_b32_e32 v40, v40, v42
	v_or_b32_e32 v41, v41, v28
	v_xor_b32_e32 v42, 32, v29
	v_or_b32_e32 v40, v40, v42
	v_xor_b32_e32 v42, 32, v30
	v_or_b32_e32 v40, v40, v42
	v_xor_b32_e32 v42, 32, v31
	v_or_b32_e32 v40, v40, v42
	v_xor_b32_e32 v42, 32, v32
	v_or_b32_e32 v40, v40, v42
	v_xor_b32_e32 v42, 32, v33
	v_or_b32_e32 v40, v40, v42
	v_xor_b32_e32 v42, 32, v34
	v_or_b32_e32 v40, v40, v42
	v_xor_b32_e32 v42, 32, v35
	v_or_b32_e32 v40, v40, v42
	v_xor_b32_e32 v42, 32, v36
	v_or_b32_e32 v40, v40, v42
	v_xor_b32_e32 v41, 0xff, v41
	v_or_b32_e32 v40, v40, v41
	v_readlane_b32 s100, v253, 63
	s_nop 0
	s_xor_b32 s100, s100, 0x100
	v_or_b32_e32 v40, s100, v40
	v_cmp_eq_u32_e32 vcc, 0, v40
	s_nop 1
	v_cndmask_b32_e64 v43, 2, 1, vcc
	v_mov_b32_e32 v44, 0x20008
	ds_write_b32 v44, v43
.Lxb_en_done:
	ds_read_b32 v2, v0
	v_readlane_b32 s7, v253, 51
	s_and_b32 s48, s6, 15
	s_waitcnt lgkmcnt(0)
	v_cmp_ne_u32_e32 vcc, 0, v2
	v_mov_b32_e32 v0, s7
	ds_read_b32 v0, v0
	s_cbranch_vccnz .LBB0_1186
	s_add_u32 s6, s2, 0x1b069200
	s_addc_u32 s7, s3, 0
	s_add_u32 s8, s2, 0x1b069400
	s_addc_u32 s9, s3, 0
	s_add_u32 s10, s2, 0x1b069500
	s_addc_u32 s11, s3, 0
	s_add_u32 s12, s2, 0x1b069600
	s_addc_u32 s13, s3, 0
	s_add_u32 s14, s2, 0x1b069700
	s_addc_u32 s15, s3, 0
	s_add_u32 s16, s2, 0x1b069800
	s_addc_u32 s17, s3, 0
	s_add_u32 s18, s2, 0x1b069900
	s_addc_u32 s19, s3, 0
	s_add_u32 s20, s2, 0x1b069a00
	s_addc_u32 s21, s3, 0
	s_add_u32 s22, s2, 0x1b069b00
	s_addc_u32 s23, s3, 0
	s_add_u32 s24, s2, 0x1b069c00
	s_addc_u32 s25, s3, 0
	s_add_u32 s26, s2, 0x1b069d00
	s_addc_u32 s27, s3, 0
	s_add_u32 s28, s2, 0x1b069e00
	s_addc_u32 s29, s3, 0
	s_add_u32 s30, s2, 0x1b069f00
	s_addc_u32 s31, s3, 0
	s_add_u32 s34, s2, 0x1b06a000
	s_addc_u32 s35, s3, 0
	s_add_u32 s36, s2, 0x1b06a100
	s_addc_u32 s37, s3, 0
	s_add_u32 s38, s2, 0x1b06a200
	s_addc_u32 s39, s3, 0
	s_add_u32 s40, s2, 0x1b06a300
	s_addc_u32 s41, s3, 0
	s_mov_b32 s50, 1
	s_branch .LBB0_1140

.LBB0_1156:
	s_or_b64 exec, exec, s[18:19]
	s_xor_b64 s[18:19], s[14:15], -1
	s_add_i32 s9, s16, 0xffffc007
	s_and_b64 s[14:15], s[10:11], exec
	s_cselect_b32 s9, s25, s9
	v_mad_i64_i32 v[24:25], s[14:15], s9, v238, v[68:69]
	s_waitcnt lgkmcnt(0)
	s_lshl_b32 s94, s8, 11
	s_mov_b32 s8, 4
	s_mov_b64 s[14:15], 0
	s_and_b64 vcc, exec, s[18:19]
	v_pk_mul_f32 v[14:15], v[14:15], v[90:91]
	v_pk_mul_f32 v[12:13], v[12:13], v[88:89]
	v_pk_add_f32 v[16:17], v[154:155], 1.0 op_sel_hi:[1,0]
	v_pk_add_f32 v[18:19], v[152:153], 1.0 op_sel_hi:[1,0]
	v_pk_mul_f32 v[14:15], v[14:15], v[16:17]
	v_pk_mul_f32 v[12:13], v[12:13], v[18:19]
	v_lshl_add_u64 v[20:21], v[70:71], 0, s[94:95]
	v_cvt_pk_bf16_f32 v12, v12, v13
	v_cvt_pk_bf16_f32 v13, v14, v15
	global_store_dwordx2 v[20:21], v[12:13], off
	s_nop 0
	v_pk_mul_f32 v[10:11], v[10:11], v[94:95]
	v_pk_mul_f32 v[8:9], v[8:9], v[92:93]
	v_pk_add_f32 v[12:13], v[158:159], 1.0 op_sel_hi:[1,0]
	v_pk_add_f32 v[14:15], v[156:157], 1.0 op_sel_hi:[1,0]
	v_pk_mul_f32 v[10:11], v[10:11], v[12:13]
	v_pk_mul_f32 v[8:9], v[8:9], v[14:15]
	s_nop 0
	v_cvt_pk_bf16_f32 v8, v8, v9
	v_cvt_pk_bf16_f32 v9, v10, v11
	global_store_dwordx2 v[20:21], v[8:9], off offset:512
	s_nop 0
	v_pk_mul_f32 v[6:7], v[6:7], v[98:99]
	v_pk_mul_f32 v[4:5], v[4:5], v[96:97]
	v_pk_add_f32 v[8:9], v[162:163], 1.0 op_sel_hi:[1,0]
	v_pk_add_f32 v[10:11], v[160:161], 1.0 op_sel_hi:[1,0]
	v_pk_mul_f32 v[6:7], v[6:7], v[8:9]
	v_pk_mul_f32 v[4:5], v[4:5], v[10:11]
	s_nop 0
	v_cvt_pk_bf16_f32 v4, v4, v5
	v_cvt_pk_bf16_f32 v5, v6, v7
	global_store_dwordx2 v[20:21], v[4:5], off offset:1024
	s_nop 0
	v_pk_mul_f32 v[2:3], v[2:3], v[102:103]
	v_pk_mul_f32 v[0:1], v[0:1], v[100:101]
	v_pk_add_f32 v[4:5], v[166:167], 1.0 op_sel_hi:[1,0]
	v_pk_add_f32 v[6:7], v[164:165], 1.0 op_sel_hi:[1,0]
	v_pk_mul_f32 v[2:3], v[2:3], v[4:5]
	v_pk_mul_f32 v[0:1], v[0:1], v[6:7]
	s_nop 0
	v_cvt_pk_bf16_f32 v0, v0, v1
	v_cvt_pk_bf16_f32 v1, v2, v3
	global_store_dwordx2 v[20:21], v[0:1], off offset:1536
	s_cbranch_vccnz .LBB0_1148

.LBB0_1173:
	global_load_dwordx4 v[12:15], v0, s[22:23]
	global_load_dwordx4 v[8:11], v0, s[22:23] offset:1024
	global_load_dwordx4 v[4:7], v0, s[22:23] offset:2048
	s_nop 0
	global_load_dwordx4 v[0:3], v0, s[22:23] offset:3072
	s_add_i32 s9, s16, 0xffffc004
	s_and_b64 s[22:23], s[10:11], exec
	s_cselect_b32 s9, s25, s9
	v_mad_i64_i32 v[168:169], s[22:23], s9, v238, v[68:69]
	s_add_i32 s9, s16, 0xffffc005
	s_and_b64 s[22:23], s[10:11], exec
	s_cselect_b32 s9, s25, s9
	v_mad_i64_i32 v[170:171], s[22:23], s9, v238, v[68:69]
	s_add_i32 s9, s16, 0xffffc006
	s_and_b64 s[22:23], s[10:11], exec
	s_cselect_b32 s9, s25, s9
	v_mad_i64_i32 v[172:173], s[22:23], s9, v238, v[68:69]
	s_add_i32 s9, s16, 0xffffc007
	s_and_b64 s[22:23], s[10:11], exec
	s_cselect_b32 s9, s25, s9
	v_mad_i64_i32 v[174:175], s[22:23], s9, v238, v[68:69]
	global_load_dwordx4 v[88:91], v[66:67], off
	global_load_dwordx4 v[92:95], v[66:67], off offset:1024
	global_load_dwordx4 v[96:99], v[66:67], off offset:2048
	global_load_dwordx4 v[100:103], v[66:67], off offset:3072
	global_load_dwordx4 v[104:107], v[168:169], off
	global_load_dwordx4 v[108:111], v[168:169], off offset:1024
	global_load_dwordx4 v[112:115], v[168:169], off offset:2048
	global_load_dwordx4 v[116:119], v[168:169], off offset:3072
	global_load_dwordx4 v[120:123], v[170:171], off
	global_load_dwordx4 v[124:127], v[170:171], off offset:1024
	global_load_dwordx4 v[128:131], v[170:171], off offset:2048
	global_load_dwordx4 v[132:135], v[170:171], off offset:3072
	global_load_dwordx4 v[136:139], v[172:173], off
	global_load_dwordx4 v[140:143], v[172:173], off offset:1024
	global_load_dwordx4 v[144:147], v[172:173], off offset:2048
	global_load_dwordx4 v[148:151], v[172:173], off offset:3072
	global_load_dwordx4 v[152:155], v[174:175], off
	global_load_dwordx4 v[156:159], v[174:175], off offset:1024
	global_load_dwordx4 v[160:163], v[174:175], off offset:2048
	global_load_dwordx4 v[164:167], v[174:175], off offset:3072
	s_waitcnt vmcnt(0)
	v_mul_f32_e32 v77, v61, v61
	v_mul_f32_e32 v78, v57, v57
	v_fmac_f32_e32 v77, v60, v60
	v_fmac_f32_e32 v78, v56, v56
	v_fmac_f32_e32 v77, v62, v62
	v_fmac_f32_e32 v78, v58, v58
	v_fmac_f32_e32 v77, v63, v63
	v_fmac_f32_e32 v78, v59, v59
	v_add_f32_e32 v77, v77, v78
	v_mul_f32_e32 v78, v53, v53
	v_fmac_f32_e32 v78, v52, v52
	v_fmac_f32_e32 v78, v54, v54
	v_fmac_f32_e32 v78, v55, v55
	v_add_f32_e32 v77, v77, v78
	v_mul_f32_e32 v78, v49, v49
	v_fmac_f32_e32 v78, v48, v48
	v_fmac_f32_e32 v78, v50, v50
	v_fmac_f32_e32 v78, v51, v51
	v_add_f32_e32 v77, v77, v78
	ds_bpermute_b32 v78, v65, v77
	s_waitcnt lgkmcnt(0)
	v_add_f32_e32 v77, v77, v78
	ds_bpermute_b32 v78, v72, v77
	s_waitcnt lgkmcnt(0)
	v_add_f32_e32 v77, v77, v78
	ds_bpermute_b32 v78, v73, v77
	s_waitcnt lgkmcnt(0)
	v_add_f32_e32 v77, v77, v78
	ds_bpermute_b32 v78, v74, v77
	s_waitcnt lgkmcnt(0)
	v_add_f32_e32 v77, v77, v78
	ds_bpermute_b32 v78, v75, v77
	s_waitcnt lgkmcnt(0)
	v_add_f32_e32 v77, v77, v78
	ds_bpermute_b32 v78, v76, v77
	s_and_saveexec_b64 s[22:23], s[6:7]
	s_cbranch_execz .LBB0_1175
	s_mov_b32 s17, s95
	s_lshl_b64 s[26:27], s[16:17], 2
	s_add_u32 s26, s76, s26
	s_addc_u32 s27, s77, s27
	s_waitcnt lgkmcnt(0)
	v_add_f32_e32 v77, v77, v78
	global_store_dword v193, v77, s[26:27]
.LBB0_1175:
	s_or_b64 exec, exec, s[22:23]
	s_add_i32 s9, s16, 0xffffc004
	s_and_b64 s[22:23], s[10:11], exec
	s_cselect_b32 s9, s25, s9
	v_mad_i64_i32 v[86:87], s[22:23], s9, v238, v[68:69]
	s_waitcnt lgkmcnt(0)
	s_lshl_b32 s94, s16, 11
	v_pk_mul_f32 v[62:63], v[62:63], v[90:91]
	v_pk_mul_f32 v[60:61], v[60:61], v[88:89]
	v_pk_add_f32 v[78:79], v[106:107], 1.0 op_sel_hi:[1,0]
	v_pk_add_f32 v[80:81], v[104:105], 1.0 op_sel_hi:[1,0]
	v_pk_mul_f32 v[62:63], v[62:63], v[78:79]
	v_pk_mul_f32 v[60:61], v[60:61], v[80:81]
	v_lshl_add_u64 v[82:83], v[70:71], 0, s[94:95]
	v_cvt_pk_bf16_f32 v60, v60, v61
	v_cvt_pk_bf16_f32 v61, v62, v63
	global_store_dwordx2 v[82:83], v[60:61], off
	s_nop 0
	v_pk_mul_f32 v[58:59], v[58:59], v[94:95]
	v_pk_mul_f32 v[56:57], v[56:57], v[92:93]
	v_pk_add_f32 v[60:61], v[110:111], 1.0 op_sel_hi:[1,0]
	v_pk_add_f32 v[62:63], v[108:109], 1.0 op_sel_hi:[1,0]
	v_pk_mul_f32 v[58:59], v[58:59], v[60:61]
	v_pk_mul_f32 v[56:57], v[56:57], v[62:63]
	s_nop 0
	v_cvt_pk_bf16_f32 v56, v56, v57
	v_cvt_pk_bf16_f32 v57, v58, v59
	global_store_dwordx2 v[82:83], v[56:57], off offset:512
	s_nop 0
	v_pk_mul_f32 v[54:55], v[54:55], v[98:99]
	v_pk_mul_f32 v[52:53], v[52:53], v[96:97]
	v_pk_add_f32 v[56:57], v[114:115], 1.0 op_sel_hi:[1,0]
	v_pk_add_f32 v[58:59], v[112:113], 1.0 op_sel_hi:[1,0]
	v_pk_mul_f32 v[54:55], v[54:55], v[56:57]
	v_pk_mul_f32 v[52:53], v[52:53], v[58:59]
	s_nop 0
	v_cvt_pk_bf16_f32 v52, v52, v53
	v_cvt_pk_bf16_f32 v53, v54, v55
	global_store_dwordx2 v[82:83], v[52:53], off offset:1024
	s_nop 0
	v_pk_mul_f32 v[50:51], v[50:51], v[102:103]
	v_pk_mul_f32 v[48:49], v[48:49], v[100:101]
	v_pk_add_f32 v[52:53], v[118:119], 1.0 op_sel_hi:[1,0]
	v_pk_add_f32 v[54:55], v[116:117], 1.0 op_sel_hi:[1,0]
	v_pk_mul_f32 v[50:51], v[50:51], v[52:53]
	v_pk_mul_f32 v[48:49], v[48:49], v[54:55]
	s_nop 0
	v_cvt_pk_bf16_f32 v48, v48, v49
	v_cvt_pk_bf16_f32 v49, v50, v51
	global_store_dwordx2 v[82:83], v[48:49], off offset:1536
	v_mul_f32_e32 v48, v45, v45
	v_mul_f32_e32 v49, v41, v41
	v_fmac_f32_e32 v48, v44, v44
	v_fmac_f32_e32 v49, v40, v40
	v_fmac_f32_e32 v48, v46, v46
	v_fmac_f32_e32 v49, v42, v42
	v_fmac_f32_e32 v48, v47, v47
	v_fmac_f32_e32 v49, v43, v43
	v_add_f32_e32 v48, v48, v49
	v_mul_f32_e32 v49, v37, v37
	v_fmac_f32_e32 v49, v36, v36
	v_fmac_f32_e32 v49, v38, v38
	v_fmac_f32_e32 v49, v39, v39
	v_add_f32_e32 v48, v48, v49
	v_mul_f32_e32 v49, v33, v33
	v_fmac_f32_e32 v49, v32, v32
	v_fmac_f32_e32 v49, v34, v34
	v_fmac_f32_e32 v49, v35, v35
	v_add_f32_e32 v48, v48, v49
	ds_bpermute_b32 v49, v65, v48
	s_waitcnt lgkmcnt(0)
	v_add_f32_e32 v48, v48, v49
	ds_bpermute_b32 v49, v72, v48
	s_waitcnt lgkmcnt(0)
	v_add_f32_e32 v48, v48, v49
	ds_bpermute_b32 v49, v73, v48
	s_waitcnt lgkmcnt(0)
	v_add_f32_e32 v48, v48, v49
	ds_bpermute_b32 v49, v74, v48
	s_waitcnt lgkmcnt(0)
	v_add_f32_e32 v48, v48, v49
	ds_bpermute_b32 v49, v75, v48
	s_waitcnt lgkmcnt(0)
	v_add_f32_e32 v48, v48, v49
	ds_bpermute_b32 v49, v76, v48
	s_and_saveexec_b64 s[22:23], s[6:7]
	s_cbranch_execz .LBB0_1177
	s_mov_b32 s21, s95
	s_lshl_b64 s[26:27], s[20:21], 2
	s_add_u32 s26, s76, s26
	s_addc_u32 s27, s77, s27
	s_waitcnt lgkmcnt(0)
	v_add_f32_e32 v48, v48, v49
	global_store_dword v193, v48, s[26:27]
.LBB0_1177:
	s_or_b64 exec, exec, s[22:23]
	s_add_i32 s9, s16, 0xffffc005
	s_and_b64 s[22:23], s[10:11], exec
	s_cselect_b32 s9, s25, s9
	v_mad_i64_i32 v[56:57], s[22:23], s9, v238, v[68:69]
	s_waitcnt lgkmcnt(0)
	s_lshl_b32 s94, s20, 11
	v_pk_mul_f32 v[46:47], v[46:47], v[90:91]
	v_pk_mul_f32 v[44:45], v[44:45], v[88:89]
	v_pk_add_f32 v[48:49], v[122:123], 1.0 op_sel_hi:[1,0]
	v_pk_add_f32 v[50:51], v[120:121], 1.0 op_sel_hi:[1,0]
	v_pk_mul_f32 v[46:47], v[46:47], v[48:49]
	v_pk_mul_f32 v[44:45], v[44:45], v[50:51]
	v_lshl_add_u64 v[52:53], v[70:71], 0, s[94:95]
	v_cvt_pk_bf16_f32 v44, v44, v45
	v_cvt_pk_bf16_f32 v45, v46, v47
	global_store_dwordx2 v[52:53], v[44:45], off
	s_nop 0
	v_pk_mul_f32 v[42:43], v[42:43], v[94:95]
	v_pk_mul_f32 v[40:41], v[40:41], v[92:93]
	v_pk_add_f32 v[44:45], v[126:127], 1.0 op_sel_hi:[1,0]
	v_pk_add_f32 v[46:47], v[124:125], 1.0 op_sel_hi:[1,0]
	v_pk_mul_f32 v[42:43], v[42:43], v[44:45]
	v_pk_mul_f32 v[40:41], v[40:41], v[46:47]
	s_nop 0
	v_cvt_pk_bf16_f32 v40, v40, v41
	v_cvt_pk_bf16_f32 v41, v42, v43
	global_store_dwordx2 v[52:53], v[40:41], off offset:512
	s_nop 0
	v_pk_mul_f32 v[38:39], v[38:39], v[98:99]
	v_pk_mul_f32 v[36:37], v[36:37], v[96:97]
	v_pk_add_f32 v[40:41], v[130:131], 1.0 op_sel_hi:[1,0]
	v_pk_add_f32 v[42:43], v[128:129], 1.0 op_sel_hi:[1,0]
	v_pk_mul_f32 v[38:39], v[38:39], v[40:41]
	v_pk_mul_f32 v[36:37], v[36:37], v[42:43]
	s_nop 0
	v_cvt_pk_bf16_f32 v36, v36, v37
	v_cvt_pk_bf16_f32 v37, v38, v39
	global_store_dwordx2 v[52:53], v[36:37], off offset:1024
	s_nop 0
	v_pk_mul_f32 v[34:35], v[34:35], v[102:103]
	v_pk_mul_f32 v[32:33], v[32:33], v[100:101]
	v_pk_add_f32 v[36:37], v[134:135], 1.0 op_sel_hi:[1,0]
	v_pk_add_f32 v[38:39], v[132:133], 1.0 op_sel_hi:[1,0]
	v_pk_mul_f32 v[34:35], v[34:35], v[36:37]
	v_pk_mul_f32 v[32:33], v[32:33], v[38:39]
	s_nop 0
	v_cvt_pk_bf16_f32 v32, v32, v33
	v_cvt_pk_bf16_f32 v33, v34, v35
	global_store_dwordx2 v[52:53], v[32:33], off offset:1536
	v_mul_f32_e32 v32, v29, v29
	v_mul_f32_e32 v33, v25, v25
	v_fmac_f32_e32 v32, v28, v28
	v_fmac_f32_e32 v33, v24, v24
	v_fmac_f32_e32 v32, v30, v30
	v_fmac_f32_e32 v33, v26, v26
	v_fmac_f32_e32 v32, v31, v31
	v_fmac_f32_e32 v33, v27, v27
	v_add_f32_e32 v32, v32, v33
	v_mul_f32_e32 v33, v21, v21
	v_fmac_f32_e32 v33, v20, v20
	v_fmac_f32_e32 v33, v22, v22
	v_fmac_f32_e32 v33, v23, v23
	v_add_f32_e32 v32, v32, v33
	v_mul_f32_e32 v33, v17, v17
	v_fmac_f32_e32 v33, v16, v16
	v_fmac_f32_e32 v33, v18, v18
	v_fmac_f32_e32 v33, v19, v19
	v_add_f32_e32 v32, v32, v33
	ds_bpermute_b32 v33, v65, v32
	s_waitcnt lgkmcnt(0)
	v_add_f32_e32 v32, v32, v33
	ds_bpermute_b32 v33, v72, v32
	s_waitcnt lgkmcnt(0)
	v_add_f32_e32 v32, v32, v33
	ds_bpermute_b32 v33, v73, v32
	s_waitcnt lgkmcnt(0)
	v_add_f32_e32 v32, v32, v33
	ds_bpermute_b32 v33, v74, v32
	s_waitcnt lgkmcnt(0)
	v_add_f32_e32 v32, v32, v33
	ds_bpermute_b32 v33, v75, v32
	s_waitcnt lgkmcnt(0)
	v_add_f32_e32 v32, v32, v33
	ds_bpermute_b32 v33, v76, v32
	s_and_saveexec_b64 s[20:21], s[6:7]
	s_cbranch_execz .LBB0_1179
	s_mov_b32 s19, s95
	s_lshl_b64 s[22:23], s[18:19], 2
	s_add_u32 s22, s76, s22
	s_addc_u32 s23, s77, s23
	s_waitcnt lgkmcnt(0)
	v_add_f32_e32 v32, v32, v33
	global_store_dword v193, v32, s[22:23]
.LBB0_1179:
	s_or_b64 exec, exec, s[20:21]
	s_add_i32 s9, s16, 0xffffc006
	s_and_b64 s[20:21], s[10:11], exec
	s_cselect_b32 s9, s25, s9
	v_mad_i64_i32 v[40:41], s[20:21], s9, v238, v[68:69]
	s_waitcnt lgkmcnt(0)
	s_lshl_b32 s94, s18, 11
	v_pk_mul_f32 v[30:31], v[30:31], v[90:91]
	v_pk_mul_f32 v[28:29], v[28:29], v[88:89]
	v_pk_add_f32 v[32:33], v[138:139], 1.0 op_sel_hi:[1,0]
	v_pk_add_f32 v[34:35], v[136:137], 1.0 op_sel_hi:[1,0]
	v_pk_mul_f32 v[30:31], v[30:31], v[32:33]
	v_pk_mul_f32 v[28:29], v[28:29], v[34:35]
	v_lshl_add_u64 v[36:37], v[70:71], 0, s[94:95]
	v_cvt_pk_bf16_f32 v28, v28, v29
	v_cvt_pk_bf16_f32 v29, v30, v31
	global_store_dwordx2 v[36:37], v[28:29], off
	s_nop 0
	v_pk_mul_f32 v[26:27], v[26:27], v[94:95]
	v_pk_mul_f32 v[24:25], v[24:25], v[92:93]
	v_pk_add_f32 v[28:29], v[142:143], 1.0 op_sel_hi:[1,0]
	v_pk_add_f32 v[30:31], v[140:141], 1.0 op_sel_hi:[1,0]
	v_pk_mul_f32 v[26:27], v[26:27], v[28:29]
	v_pk_mul_f32 v[24:25], v[24:25], v[30:31]
	s_nop 0
	v_cvt_pk_bf16_f32 v24, v24, v25
	v_cvt_pk_bf16_f32 v25, v26, v27
	global_store_dwordx2 v[36:37], v[24:25], off offset:512
	s_nop 0
	v_pk_mul_f32 v[22:23], v[22:23], v[98:99]
	v_pk_mul_f32 v[20:21], v[20:21], v[96:97]
	v_pk_add_f32 v[24:25], v[146:147], 1.0 op_sel_hi:[1,0]
	v_pk_add_f32 v[26:27], v[144:145], 1.0 op_sel_hi:[1,0]
	v_pk_mul_f32 v[22:23], v[22:23], v[24:25]
	v_pk_mul_f32 v[20:21], v[20:21], v[26:27]
	s_nop 0
	v_cvt_pk_bf16_f32 v20, v20, v21
	v_cvt_pk_bf16_f32 v21, v22, v23
	global_store_dwordx2 v[36:37], v[20:21], off offset:1024
	s_nop 0
	v_pk_mul_f32 v[18:19], v[18:19], v[102:103]
	v_pk_mul_f32 v[16:17], v[16:17], v[100:101]
	v_pk_add_f32 v[20:21], v[150:151], 1.0 op_sel_hi:[1,0]
	v_pk_add_f32 v[22:23], v[148:149], 1.0 op_sel_hi:[1,0]
	v_pk_mul_f32 v[18:19], v[18:19], v[20:21]
	v_pk_mul_f32 v[16:17], v[16:17], v[22:23]
	s_nop 0
	v_cvt_pk_bf16_f32 v16, v16, v17
	v_cvt_pk_bf16_f32 v17, v18, v19
	global_store_dwordx2 v[36:37], v[16:17], off offset:1536
	v_mul_f32_e32 v16, v13, v13
	v_mul_f32_e32 v17, v9, v9
	v_fmac_f32_e32 v16, v12, v12
	v_fmac_f32_e32 v17, v8, v8
	v_fmac_f32_e32 v16, v14, v14
	v_fmac_f32_e32 v17, v10, v10
	v_fmac_f32_e32 v16, v15, v15
	v_fmac_f32_e32 v17, v11, v11
	v_add_f32_e32 v16, v16, v17
	v_mul_f32_e32 v17, v5, v5
	v_fmac_f32_e32 v17, v4, v4
	v_fmac_f32_e32 v17, v6, v6
	v_fmac_f32_e32 v17, v7, v7
	v_add_f32_e32 v16, v16, v17
	v_mul_f32_e32 v17, v1, v1
	v_fmac_f32_e32 v17, v0, v0
	v_fmac_f32_e32 v17, v2, v2
	v_fmac_f32_e32 v17, v3, v3
	v_add_f32_e32 v16, v16, v17
	ds_bpermute_b32 v17, v65, v16
	s_waitcnt lgkmcnt(0)
	v_add_f32_e32 v16, v16, v17
	ds_bpermute_b32 v17, v72, v16
	s_waitcnt lgkmcnt(0)
	v_add_f32_e32 v16, v16, v17
	ds_bpermute_b32 v17, v73, v16
	s_waitcnt lgkmcnt(0)
	v_add_f32_e32 v16, v16, v17
	ds_bpermute_b32 v17, v74, v16
	s_waitcnt lgkmcnt(0)
	v_add_f32_e32 v16, v16, v17
	ds_bpermute_b32 v17, v75, v16
	s_waitcnt lgkmcnt(0)
	v_add_f32_e32 v16, v16, v17
	ds_bpermute_b32 v17, v76, v16
	s_and_saveexec_b64 s[18:19], s[6:7]
	s_cbranch_execz .LBB0_1156
	s_mov_b32 s9, s95
	s_lshl_b64 s[20:21], s[8:9], 2
	s_add_u32 s20, s76, s20
	s_addc_u32 s21, s77, s21
	s_waitcnt lgkmcnt(0)
	v_add_f32_e32 v16, v16, v17
	global_store_dword v193, v16, s[20:21]
	s_branch .LBB0_1156

.LBB0_1202:
	s_andn2_saveexec_b64 s[8:9], s[8:9]
	s_cbranch_execz .LBB0_1222
	s_mov_b64 s[8:9], exec
	s_cmp_lt_i32 s54, 1
	s_cbranch_scc1 .Lxb_wb
	s_and_b32 s100, s54, 7
	s_lshr_b32 s100, 0xd0, s100
	s_bitcmp1_b32 s100, 0
	s_cbranch_scc0 .Lxb_wb
	v_mov_b32_e32 v20, 0x20008
	ds_read_b32 v20, v20
	s_waitcnt lgkmcnt(0)
	v_readfirstlane_b32 s100, v20
	s_nop 0
	s_cmp_eq_u32 s100, 1
	s_cbranch_scc1 .Lxb_nowb
.Lxb_wb:
	buffer_wbl2 sc1
.Lxb_nowb:
	s_waitcnt lgkmcnt(0)
	s_waitcnt vmcnt(0)
	v_mbcnt_lo_u32_b32 v1, s8, 0
	v_mbcnt_hi_u32_b32 v1, s9, v1
	v_cmp_eq_u32_e32 vcc, 0, v1
	s_and_saveexec_b64 s[10:11], vcc
	s_cbranch_execz .LBB0_1205
	s_bcnt1_i32_b64 s8, s[8:9]
	v_mov_b32_e32 v2, s8
	v_mov_b32_e32 v3, 0x1b06c000
	global_atomic_add v2, v3, v2, s[2:3] offset:1024 sc0

.LBB0_1234:
	s_or_b64 exec, exec, s[0:1]
	s_mov_b64 s[2:3], s[52:53]
	v_mov_b32_e32 v0, v220
	s_barrier
	s_nop 0
	v_cmp_eq_u32_e32 vcc, 0, v0
	s_and_saveexec_b64 s[0:1], vcc
	s_cbranch_execz .LBB0_1237
	s_mov_b64 s[6:7], exec
	v_mbcnt_lo_u32_b32 v0, s6, 0
	v_mbcnt_hi_u32_b32 v0, s7, v0
	v_cmp_eq_u32_e32 vcc, 0, v0
	s_getreg_b32 s8, hwreg(HW_REG_XCC_ID, 0, 4)
	s_and_b64 s[10:11], exec, vcc
	s_mov_b64 exec, s[10:11]
	s_cbranch_execz .LBB0_1237
	s_load_dwordx2 s[2:3], s[2:3], 0xd8
	s_lshl_b32 s8, s8, 8
	s_and_b32 s8, s8, 0xf00
	v_mov_b32_e32 v1, 0x1b069000
	s_waitcnt lgkmcnt(0)
	s_add_u32 s2, s2, s8
	s_addc_u32 s3, s3, 0
	s_bcnt1_i32_b64 s6, s[6:7]
	v_mov_b32_e32 v0, s6
	global_atomic_add v1, v0, s[2:3] offset:1024
	v_readlane_b32 s6, v253, 0
	s_and_b32 s6, s6, 7
	s_lshl_b32 s6, 1, s6
	v_mov_b32_e32 v0, s6
	global_atomic_or v1, v0, s[2:3] offset:1088
